# mixer phase order split by blockIdx bit 5 (groups of four ranks)
# speedup vs baseline: 1.0131x; 1.0027x over previous
; #define LAS __attribute__((address_space(3)))
; #define LAUNDER() int tp = TID0(); const int tid = tp, lane = tp & 63, wave = __builtin_amdgcn_readfirstlane(tp >> 6); (void)tid; (void)lane; (void)wave
; __global__ void __launch_bounds__(512) fwd_kernel(Args a) {
;     ...
;         if (IN(pb + 2)) {
;             if (EN_B) { LAUNDER(); LAS char* vt = (LAS char*)lds + wave * 16384;
;                 (void)vt; for (int u = blockIdx.x; u < 256; u += G) { mixerB2_unit(u, l, PROJ, YC, a.in[6] + l * 128, a.in[7] + l * 64, KMAX + l * 1024, (LAS char*)lds, tid, wave, lane); } __syncthreads(); }
;             if (EN_S1) { LAUNDER(); __syncthreads();
;                 for (int u = blockIdx.x; u < 256; u += G) ssd_part1_unit(u, PROJ, DT, H, WDT + l * 16384, a.in[11] + l * 8, a.in[8] + l * 5 * 768, a.in[9] + l * 768, a.in[10] + l * 8, STATES, TOT, lds, tid, wave, lane);
;                 __syncthreads(); }
;             if (EN_A) { LAUNDER(); LAS char* vt = (LAS char*)lds + wave * 16384;
;                 for (int u = blockIdx.x; u < 512; u += G) { mixerA1_unit(u, PROJ, YC, LPA, KMAX + l * 1024, vt, wave, lane); } }
;             if (EN_D) { LAUNDER(); LAS char* vt = (LAS char*)lds + wave * 16384;
;                 int hcur = -1; float rmax = 0.f;
;                 for (int u = blockIdx.x; u < 512; u += G) { const int hd = (u >> 4) & 3; if (hd != hcur) { rmax = d_stage_rpb(a.in[14] + l * 4 * 15 * 31, hd, vt, lane); hcur = hd; }
;                     mixerD2_unit(u, PROJ, YC, rmax, KMAX + l * 1024, vt, wave, lane); } }
;         }
.Lmx_b:
	s_cmp_eq_u32 s101, 0
	s_cbranch_scc0 .Lmx_b_go
	s_bitcmp1_b32 s66, 5
	s_cbranch_scc0 .Lmx_b_go
	s_mov_b32 s101, 1
	v_readlane_b32 s0, v253, 56
	v_readlane_b32 s1, v253, 57
	s_nop 1
	v_cndmask_b32_e64 v6, 0, 1, s[0:1]
	s_nop 0
	v_cmp_ne_u32_e64 s[36:37], 1, v6
	s_branch .LBB0_262
